# latency-trim stack with the P5 epilogue reworked: row groups 2-6 prefetched in the K-loop, 7-8 issued at the epilogue top, shfl_xor row sums via permlane16/32 swap
# baseline (speedup 1.0000x reference)
; __device__ __forceinline__ f32x4 bf4_to_f32(u32x2 w) { f32x4 r; r[0] = __uint_as_float(w.x << 16); r[1] = __uint_as_float(w.x & 0xffff0000u); r[2] = __uint_as_float(w.y << 16); r[3] = __uint_as_float(w.y & 0xffff0000u); return r; }
;     __device__ __forceinline__ void fused(f32x4 (&acc)[2][2][4][2], const Unit& u, int wr, int wc, int fr, int fq, PG8_LAS unsigned char* lds, int wid, int lane) const {
;     ...
;             for (int m = 0; m < 4; ++m) { const int r = ai * HALF + wr * 64 + m * 16 + fr; const size_t off = (size_t)(u.pm * BM + r) * 2048 + col0; float s = 0.f;
;                 const float rr = __builtin_amdgcn_rcpf(r2[ai * 4 + m] * (1.0f / 2048.0f) + 1e-5f);
; #pragma unroll
;                 for (int bj = 0; bj < 2; ++bj)
; #pragma unroll
;                     for (int n = 0; n < 2; ++n) { const f32x4 bs = bf4_to_f32(*(const u32x2*)(base + off + bj * HALF + n * 16)); const f32x4 o = bs + acc[ai][bj][m][n] * rr; acc[ai][bj][m][n] = o;
.LBB0_1031:
	s_cmpk_eq_i32 s29, 118
	s_cbranch_scc0 .Lp5pf_skip
	s_lshl_b32 s46, s64, 8
	s_lshl_b32 s47, s18, 5
	s_lshl_b32 s48, s16, 8
	s_or_b32 s48, s48, s47
	v_add_u32_e32 v216, s46, v162
	v_ashrrev_i32_e32 v217, 31, v216
	v_lshlrev_b64 v[216:217], 12, v[216:217]
	v_lshl_add_u64 v[216:217], s[70:71], 0, v[216:217]
	v_and_or_b32 v192, v138, 12, s48
	v_lshlrev_b32_e32 v192, 1, v192
	v_mov_b32_e32 v193, 0
	v_lshl_add_u64 v[216:217], v[216:217], 0, v[192:193]
	s_mov_b64 s[46:47], 0x10000
	v_lshl_add_u64 v[192:193], v[216:217], 0, s[46:47]
	global_load_dwordx2 v[218:219], v[192:193], off
	global_load_dwordx2 v[220:221], v[192:193], off offset:32
	global_load_dwordx2 v[222:223], v[192:193], off offset:256
	global_load_dwordx2 v[224:225], v[192:193], off offset:288
	s_mov_b64 s[46:47], 0x20000
	v_lshl_add_u64 v[192:193], v[216:217], 0, s[46:47]
	global_load_dwordx2 v[226:227], v[192:193], off
	global_load_dwordx2 v[228:229], v[192:193], off offset:32
	global_load_dwordx2 v[230:231], v[192:193], off offset:256
	global_load_dwordx2 v[232:233], v[192:193], off offset:288
	s_mov_b64 s[46:47], 0x30000
	v_lshl_add_u64 v[192:193], v[216:217], 0, s[46:47]
	global_load_dwordx2 v[234:235], v[192:193], off
	global_load_dwordx2 v[236:237], v[192:193], off offset:32
	global_load_dwordx2 v[238:239], v[192:193], off offset:256
	global_load_dwordx2 v[240:241], v[192:193], off offset:288
	s_mov_b64 s[46:47], 0x80000
	v_lshl_add_u64 v[192:193], v[216:217], 0, s[46:47]
	global_load_dwordx2 v[244:245], v[192:193], off
	global_load_dwordx2 v[246:247], v[192:193], off offset:32
	global_load_dwordx2 v[248:249], v[192:193], off offset:256
	global_load_dwordx2 v[250:251], v[192:193], off offset:288
	s_mov_b64 s[46:47], 0x90000
	v_lshl_add_u64 v[192:193], v[216:217], 0, s[46:47]
	global_load_dwordx2 v[252:253], v[192:193], off
	global_load_dwordx2 v[254:255], v[192:193], off offset:32
	global_load_dwordx2 v[216:217], v[192:193], off offset:256
	s_nop 0
	global_load_dwordx2 v[192:193], v[192:193], off offset:288

; __device__ __forceinline__ f32x4 bf4_to_f32(u32x2 w) { f32x4 r; r[0] = __uint_as_float(w.x << 16); r[1] = __uint_as_float(w.x & 0xffff0000u); r[2] = __uint_as_float(w.y << 16); r[3] = __uint_as_float(w.y & 0xffff0000u); return r; }
;     __device__ __forceinline__ void fused(f32x4 (&acc)[2][2][4][2], const Unit& u, int wr, int wc, int fr, int fq, PG8_LAS unsigned char* lds, int wid, int lane) const {
;     ...
;         for (int g = 0; g < 8; ++g) r2[g] = __hip_atomic_load(rs2 + u.pm * BM + (g >> 2) * HALF + wr * 64 + (g & 3) * 16 + fr, __ATOMIC_RELAXED, __HIP_MEMORY_SCOPE_AGENT);
; #pragma unroll
;         for (int ai = 0; ai < 2; ++ai)
; #pragma unroll
;             for (int m = 0; m < 4; ++m) { const int r = ai * HALF + wr * 64 + m * 16 + fr; const size_t off = (size_t)(u.pm * BM + r) * 2048 + col0; float s = 0.f;
;                 const float rr = __builtin_amdgcn_rcpf(r2[ai * 4 + m] * (1.0f / 2048.0f) + 1e-5f);
; #pragma unroll
;                 for (int bj = 0; bj < 2; ++bj)
; #pragma unroll
;                     for (int n = 0; n < 2; ++n) { const f32x4 bs = bf4_to_f32(*(const u32x2*)(base + off + bj * HALF + n * 16)); const f32x4 o = bs + acc[ai][bj][m][n] * rr; acc[ai][bj][m][n] = o;
;                         s += (o[0] * o[0] + o[1] * o[1]) + (o[2] * o[2] + o[3] * o[3]); }
;                 s += __shfl_xor(s, 16); s += __shfl_xor(s, 32);
;                 if (fq == 0) P[r * 4 + wc] = s; }
.LBB0_1034:
	s_lshl_b32 s0, s64, 8
	s_ashr_i32 s1, s0, 31
	s_lshl_b32 s4, s18, 5
	s_lshl_b64 s[2:3], s[0:1], 2
	s_add_u32 s1, s6, s2
	s_addc_u32 s3, s7, s3
	s_lshl_b32 s2, s24, 2
	s_add_u32 s2, s1, s2
	s_addc_u32 s3, s3, 0
	s_lshl_b32 s1, s16, 8
	v_add_u32_e32 v130, s0, v162
	s_or_b32 s1, s1, s4
	v_ashrrev_i32_e32 v131, 31, v130
	v_and_or_b32 v160, v138, 12, s1
	v_lshlrev_b64 v[132:133], 12, v[130:131]
	v_mov_b32_e32 v141, 0
	v_lshl_add_u64 v[132:133], s[70:71], 0, v[132:133]
	v_lshlrev_b32_e32 v140, 1, v160
	v_lshlrev_b32_e32 v1, 2, v1
	v_lshl_add_u64 v[132:133], v[132:133], 0, v[140:141]
	v_mov_b64_e32 v[212:213], v[132:133]
	s_barrier
	global_load_dword v137, v1, s[2:3] sc1
	global_load_dword v134, v1, s[2:3] offset:64 sc1
	global_load_dword v136, v1, s[2:3] offset:128 sc1
	global_load_dword v139, v1, s[2:3] offset:192 sc1
	global_load_dword v142, v1, s[2:3] offset:512 sc1
	global_load_dword v144, v1, s[2:3] offset:576 sc1
	global_load_dword v146, v1, s[2:3] offset:640 sc1
	s_nop 0
	global_load_dword v1, v1, s[2:3] offset:704 sc1
	s_nop 0
	global_load_dwordx2 v[148:149], v[132:133], off
	global_load_dwordx2 v[150:151], v[132:133], off offset:32
	global_load_dwordx2 v[152:153], v[132:133], off offset:256
	s_nop 0
	global_load_dwordx2 v[132:133], v[132:133], off offset:288
	s_mov_b64 s[98:99], 0xa0000
	v_lshl_add_u64 v[214:215], v[212:213], 0, s[98:99]
	global_load_dwordx2 v[196:197], v[214:215], off
	global_load_dwordx2 v[198:199], v[214:215], off offset:32
	global_load_dwordx2 v[200:201], v[214:215], off offset:256
	global_load_dwordx2 v[202:203], v[214:215], off offset:288
	s_mov_b64 s[98:99], 0xb0000
	v_lshl_add_u64 v[214:215], v[212:213], 0, s[98:99]
	global_load_dwordx2 v[204:205], v[214:215], off
	global_load_dwordx2 v[206:207], v[214:215], off offset:32
	global_load_dwordx2 v[208:209], v[214:215], off offset:256
	global_load_dwordx2 v[210:211], v[214:215], off offset:288
	v_mbcnt_lo_u32_b32 v138, -1, 0
	v_mbcnt_hi_u32_b32 v143, -1, v138
	v_and_b32_e32 v145, 64, v143
	v_xor_b32_e32 v138, 16, v143
	v_add_u32_e32 v145, 64, v145
	v_mov_b32_e32 v135, 0x3727c5ac
	v_cmp_lt_i32_e32 vcc, v138, v145
	s_lshl_b32 s1, s18, 2
	s_add_i32 s1, s1, 0
	v_cndmask_b32_e32 v138, v143, v138, vcc
	v_lshlrev_b32_e32 v161, 2, v138
	s_waitcnt vmcnt(8)
	v_fmamk_f32 v137, v137, 0x3a000000, v135
	v_rcp_f32_e32 v138, v137
	v_lshlrev_b32_e32 v154, 16, v148
	v_and_b32_e32 v155, 0xffff0000, v148
	v_lshlrev_b32_e32 v148, 16, v149
	v_and_b32_e32 v149, 0xffff0000, v149
	v_lshlrev_b32_e32 v156, 16, v150
	v_and_b32_e32 v157, 0xffff0000, v150
	v_lshlrev_b32_e32 v150, 16, v151
	v_and_b32_e32 v151, 0xffff0000, v151
	v_lshlrev_b32_e32 v158, 16, v152
	v_and_b32_e32 v159, 0xffff0000, v152
	v_lshlrev_b32_e32 v152, 16, v153
	v_and_b32_e32 v153, 0xffff0000, v153
	v_lshlrev_b32_e32 v164, 16, v132
	v_and_b32_e32 v165, 0xffff0000, v132
	v_lshlrev_b32_e32 v132, 16, v133
	v_and_b32_e32 v133, 0xffff0000, v133
	v_pk_fma_f32 v[128:129], v[128:129], v[138:139], v[148:149] op_sel_hi:[1,0,1]
	v_pk_fma_f32 v[126:127], v[126:127], v[138:139], v[154:155] op_sel_hi:[1,0,1]
	v_pk_fma_f32 v[124:125], v[124:125], v[138:139], v[150:151] op_sel_hi:[1,0,1]
	v_pk_fma_f32 v[122:123], v[122:123], v[138:139], v[156:157] op_sel_hi:[1,0,1]
	v_pk_fma_f32 v[120:121], v[120:121], v[138:139], v[152:153] op_sel_hi:[1,0,1]
	v_pk_fma_f32 v[118:119], v[118:119], v[138:139], v[158:159] op_sel_hi:[1,0,1]
	v_pk_fma_f32 v[116:117], v[116:117], v[138:139], v[132:133] op_sel_hi:[1,0,1]
	v_pk_fma_f32 v[114:115], v[114:115], v[138:139], v[164:165] op_sel_hi:[1,0,1]
	v_mul_f32_e32 v132, v127, v127
	v_mul_f32_e32 v133, v129, v129
	v_mul_f32_e32 v137, v123, v123
	v_mul_f32_e32 v138, v125, v125
	v_mul_f32_e32 v147, v119, v119
	v_mul_f32_e32 v148, v121, v121
	v_fmac_f32_e32 v132, v126, v126
	v_fmac_f32_e32 v133, v128, v128
	v_fmac_f32_e32 v137, v122, v122
	v_fmac_f32_e32 v138, v124, v124
	v_mul_f32_e32 v149, v115, v115
	v_mul_f32_e32 v150, v117, v117
	v_fmac_f32_e32 v147, v118, v118
	v_fmac_f32_e32 v148, v120, v120
	v_add_f32_e32 v132, v132, v133
	v_add_f32_e32 v133, v137, v138
	v_fmac_f32_e32 v149, v114, v114
	v_fmac_f32_e32 v150, v116, v116
	v_add_f32_e32 v137, v147, v148
	v_add_f32_e32 v132, v132, v133
	v_add_f32_e32 v132, v132, v137
	v_add_f32_e32 v133, v149, v150
	v_add_f32_e32 v132, v132, v133
	v_mov_b32_e32 v133, v132
	s_nop 1
	v_permlane16_swap_b32_e32 v133, v132
	v_xor_b32_e32 v137, 32, v143
	v_cmp_lt_i32_e32 vcc, v137, v145
	s_waitcnt lgkmcnt(0)
	v_add_f32_e32 v132, v132, v133
	v_cndmask_b32_e32 v137, v143, v137, vcc
	v_lshlrev_b32_e32 v163, 2, v137
	v_mov_b32_e32 v133, v132
	s_nop 1
	v_permlane32_swap_b32_e32 v133, v132
	v_cmp_gt_u32_e32 vcc, 16, v194
	s_and_saveexec_b64 s[2:3], vcc
	s_cbranch_execz .LBB0_1036
	v_lshl_add_u32 v137, v162, 4, s1
	s_waitcnt lgkmcnt(0)
	v_add_f32_e32 v132, v132, v133
	ds_write_b32 v137, v132
; __device__ __forceinline__ f32x4 bf4_to_f32(u32x2 w) { f32x4 r; r[0] = __uint_as_float(w.x << 16); r[1] = __uint_as_float(w.x & 0xffff0000u); r[2] = __uint_as_float(w.y << 16); r[3] = __uint_as_float(w.y & 0xffff0000u); return r; }
;     __device__ __forceinline__ void fused(f32x4 (&acc)[2][2][4][2], const Unit& u, int wr, int wc, int fr, int fq, PG8_LAS unsigned char* lds, int wid, int lane) const {
;     ...
;             for (int m = 0; m < 4; ++m) { const int r = ai * HALF + wr * 64 + m * 16 + fr; const size_t off = (size_t)(u.pm * BM + r) * 2048 + col0; float s = 0.f;
;                 const float rr = __builtin_amdgcn_rcpf(r2[ai * 4 + m] * (1.0f / 2048.0f) + 1e-5f);
; #pragma unroll
;                 for (int bj = 0; bj < 2; ++bj)
; #pragma unroll
;                     for (int n = 0; n < 2; ++n) { const f32x4 bs = bf4_to_f32(*(const u32x2*)(base + off + bj * HALF + n * 16)); const f32x4 o = bs + acc[ai][bj][m][n] * rr; acc[ai][bj][m][n] = o;
;                         s += (o[0] * o[0] + o[1] * o[1]) + (o[2] * o[2] + o[3] * o[3]); }
;                 s += __shfl_xor(s, 16); s += __shfl_xor(s, 32);
;                 if (fq == 0) P[r * 4 + wc] = s; }
.LBB0_1036:
	s_or_b64 exec, exec, s[2:3]
	v_or_b32_e32 v137, 16, v162
	v_add_u32_e32 v132, s0, v137
	s_waitcnt lgkmcnt(0)
	v_ashrrev_i32_e32 v133, 31, v132
	v_lshlrev_b64 v[148:149], 12, v[132:133]
	v_lshl_add_u64 v[148:149], s[70:71], 0, v[148:149]
	v_lshl_add_u64 v[148:149], v[148:149], 0, v[140:141]
	v_mov_b64_e32 v[150:151], v[218:219]
	v_mov_b64_e32 v[152:153], v[220:221]
	v_mov_b64_e32 v[154:155], v[222:223]
	v_mov_b64_e32 v[148:149], v[224:225]
	s_nop 0
	v_fmac_f32_e32 v135, 0x3a000000, v134
	v_rcp_f32_e32 v134, v135
	s_waitcnt vmcnt(3)
	v_lshlrev_b32_e32 v156, 16, v150
	v_and_b32_e32 v157, 0xffff0000, v150
	v_lshlrev_b32_e32 v150, 16, v151
	v_and_b32_e32 v151, 0xffff0000, v151
	s_waitcnt vmcnt(2)
	v_lshlrev_b32_e32 v158, 16, v152
	v_and_b32_e32 v159, 0xffff0000, v152
	v_lshlrev_b32_e32 v152, 16, v153
	v_and_b32_e32 v153, 0xffff0000, v153
	s_waitcnt vmcnt(1)
	v_lshlrev_b32_e32 v164, 16, v154
	v_and_b32_e32 v165, 0xffff0000, v154
	v_lshlrev_b32_e32 v154, 16, v155
	v_and_b32_e32 v155, 0xffff0000, v155
	s_waitcnt vmcnt(0)
	v_lshlrev_b32_e32 v166, 16, v148
	v_and_b32_e32 v167, 0xffff0000, v148
	v_lshlrev_b32_e32 v148, 16, v149
	v_and_b32_e32 v149, 0xffff0000, v149
	v_pk_fma_f32 v[112:113], v[112:113], v[134:135], v[150:151] op_sel_hi:[1,0,1]
	v_pk_fma_f32 v[110:111], v[110:111], v[134:135], v[156:157] op_sel_hi:[1,0,1]
	v_pk_fma_f32 v[108:109], v[108:109], v[134:135], v[152:153] op_sel_hi:[1,0,1]
	v_pk_fma_f32 v[106:107], v[106:107], v[134:135], v[158:159] op_sel_hi:[1,0,1]
	v_pk_fma_f32 v[104:105], v[104:105], v[134:135], v[154:155] op_sel_hi:[1,0,1]
	v_pk_fma_f32 v[102:103], v[102:103], v[134:135], v[164:165] op_sel_hi:[1,0,1]
	v_pk_fma_f32 v[100:101], v[100:101], v[134:135], v[148:149] op_sel_hi:[1,0,1]
	v_pk_fma_f32 v[98:99], v[98:99], v[134:135], v[166:167] op_sel_hi:[1,0,1]
	v_mul_f32_e32 v134, v111, v111
	v_mul_f32_e32 v135, v113, v113
	v_mul_f32_e32 v138, v107, v107
	v_mul_f32_e32 v141, v109, v109
	v_mul_f32_e32 v143, v103, v103
	v_mul_f32_e32 v145, v105, v105
	v_fmac_f32_e32 v134, v110, v110
	v_fmac_f32_e32 v135, v112, v112
	v_fmac_f32_e32 v138, v106, v106
	v_fmac_f32_e32 v141, v108, v108
	v_mul_f32_e32 v147, v99, v99
	v_mul_f32_e32 v148, v101, v101
	v_fmac_f32_e32 v143, v102, v102
	v_fmac_f32_e32 v145, v104, v104
	v_add_f32_e32 v134, v134, v135
	v_add_f32_e32 v135, v138, v141
	v_fmac_f32_e32 v147, v98, v98
	v_fmac_f32_e32 v148, v100, v100
	v_add_f32_e32 v138, v143, v145
	v_add_f32_e32 v134, v134, v135
	v_add_f32_e32 v134, v134, v138
	v_add_f32_e32 v135, v147, v148
	v_add_f32_e32 v134, v134, v135
	v_mov_b32_e32 v135, v134
	s_nop 1
	v_permlane16_swap_b32_e32 v135, v134
	s_waitcnt lgkmcnt(0)
	v_add_f32_e32 v134, v134, v135
	v_mov_b32_e32 v135, v134
	s_nop 1
	v_permlane32_swap_b32_e32 v135, v134
	s_and_saveexec_b64 s[2:3], vcc
	s_cbranch_execz .LBB0_1038
	v_lshl_add_u32 v137, v137, 4, s1
	s_waitcnt lgkmcnt(0)
	v_add_f32_e32 v134, v134, v135
	ds_write_b32 v137, v134
.LBB0_1038:
	s_or_b64 exec, exec, s[2:3]
	v_or_b32_e32 v143, 32, v162
	v_add_u32_e32 v134, s0, v143
	s_waitcnt lgkmcnt(0)
	v_ashrrev_i32_e32 v135, 31, v134
	v_lshlrev_b64 v[148:149], 12, v[134:135]
	v_lshl_add_u64 v[148:149], s[70:71], 0, v[148:149]
	v_mov_b32_e32 v141, 0
	v_lshl_add_u64 v[148:149], v[148:149], 0, v[140:141]
	v_mov_b64_e32 v[150:151], v[226:227]
	v_mov_b64_e32 v[152:153], v[228:229]
	v_mov_b64_e32 v[154:155], v[230:231]
	v_mov_b64_e32 v[148:149], v[232:233]
	s_nop 0
	v_mov_b32_e32 v138, 0x3727c5ac
	v_fmamk_f32 v136, v136, 0x3a000000, v138
	v_rcp_f32_e32 v156, v136
	s_waitcnt vmcnt(3)
	v_lshlrev_b32_e32 v136, 16, v150
	v_and_b32_e32 v137, 0xffff0000, v150
	v_lshlrev_b32_e32 v150, 16, v151
	v_and_b32_e32 v151, 0xffff0000, v151
	s_waitcnt vmcnt(2)
	v_lshlrev_b32_e32 v158, 16, v152
	v_and_b32_e32 v159, 0xffff0000, v152
	v_lshlrev_b32_e32 v152, 16, v153
	v_and_b32_e32 v153, 0xffff0000, v153
	s_waitcnt vmcnt(1)
	v_lshlrev_b32_e32 v164, 16, v154
	v_and_b32_e32 v165, 0xffff0000, v154
	v_lshlrev_b32_e32 v154, 16, v155
	v_and_b32_e32 v155, 0xffff0000, v155
	s_waitcnt vmcnt(0)
	v_lshlrev_b32_e32 v166, 16, v148
	v_and_b32_e32 v167, 0xffff0000, v148
	v_pk_fma_f32 v[96:97], v[96:97], v[156:157], v[150:151] op_sel_hi:[1,0,1]
	v_pk_fma_f32 v[136:137], v[94:95], v[156:157], v[136:137] op_sel_hi:[1,0,1]
	v_pk_fma_f32 v[92:93], v[92:93], v[156:157], v[152:153] op_sel_hi:[1,0,1]
	v_pk_fma_f32 v[94:95], v[90:91], v[156:157], v[158:159] op_sel_hi:[1,0,1]
	v_lshlrev_b32_e32 v148, 16, v149
	v_and_b32_e32 v149, 0xffff0000, v149
	v_pk_fma_f32 v[88:89], v[88:89], v[156:157], v[154:155] op_sel_hi:[1,0,1]
	v_pk_fma_f32 v[90:91], v[86:87], v[156:157], v[164:165] op_sel_hi:[1,0,1]
	v_pk_fma_f32 v[86:87], v[82:83], v[156:157], v[166:167] op_sel_hi:[1,0,1]
	v_mul_f32_e32 v82, v137, v137
	v_mul_f32_e32 v83, v97, v97
	v_mul_f32_e32 v145, v95, v95
	v_mul_f32_e32 v147, v93, v93
	v_pk_fma_f32 v[84:85], v[84:85], v[156:157], v[148:149] op_sel_hi:[1,0,1]
	v_mul_f32_e32 v148, v91, v91
	v_mul_f32_e32 v149, v89, v89
	v_fmac_f32_e32 v82, v136, v136
	v_fmac_f32_e32 v83, v96, v96
	v_fmac_f32_e32 v145, v94, v94
	v_fmac_f32_e32 v147, v92, v92
	v_mul_f32_e32 v150, v87, v87
	v_mul_f32_e32 v151, v85, v85
	v_fmac_f32_e32 v148, v90, v90
	v_fmac_f32_e32 v149, v88, v88
	v_add_f32_e32 v82, v82, v83
	v_add_f32_e32 v83, v145, v147
	v_fmac_f32_e32 v150, v86, v86
	v_fmac_f32_e32 v151, v84, v84
	v_add_f32_e32 v145, v148, v149
	v_add_f32_e32 v82, v82, v83
	v_add_f32_e32 v82, v82, v145
	v_add_f32_e32 v83, v150, v151
	v_add_f32_e32 v82, v82, v83
	v_mov_b32_e32 v83, v82
	s_nop 1
	v_permlane16_swap_b32_e32 v83, v82
	s_waitcnt lgkmcnt(0)
	v_add_f32_e32 v82, v82, v83
	v_mov_b32_e32 v83, v82
	s_nop 1
	v_permlane32_swap_b32_e32 v83, v82
	s_and_saveexec_b64 s[2:3], vcc
	s_cbranch_execz .LBB0_1040
	v_lshl_add_u32 v143, v143, 4, s1
	s_waitcnt lgkmcnt(0)
	v_add_f32_e32 v82, v82, v83
	ds_write_b32 v143, v82
; __device__ __forceinline__ f32x4 bf4_to_f32(u32x2 w) { f32x4 r; r[0] = __uint_as_float(w.x << 16); r[1] = __uint_as_float(w.x & 0xffff0000u); r[2] = __uint_as_float(w.y << 16); r[3] = __uint_as_float(w.y & 0xffff0000u); return r; }
;     __device__ __forceinline__ void fused(f32x4 (&acc)[2][2][4][2], const Unit& u, int wr, int wc, int fr, int fq, PG8_LAS unsigned char* lds, int wid, int lane) const {
;     ...
;             for (int m = 0; m < 4; ++m) { const int r = ai * HALF + wr * 64 + m * 16 + fr; const size_t off = (size_t)(u.pm * BM + r) * 2048 + col0; float s = 0.f;
;                 const float rr = __builtin_amdgcn_rcpf(r2[ai * 4 + m] * (1.0f / 2048.0f) + 1e-5f);
; #pragma unroll
;                 for (int bj = 0; bj < 2; ++bj)
; #pragma unroll
;                     for (int n = 0; n < 2; ++n) { const f32x4 bs = bf4_to_f32(*(const u32x2*)(base + off + bj * HALF + n * 16)); const f32x4 o = bs + acc[ai][bj][m][n] * rr; acc[ai][bj][m][n] = o;
;                         s += (o[0] * o[0] + o[1] * o[1]) + (o[2] * o[2] + o[3] * o[3]); }
;                 s += __shfl_xor(s, 16); s += __shfl_xor(s, 32);
;                 if (fq == 0) P[r * 4 + wc] = s; }
.LBB0_1040:
	s_or_b64 exec, exec, s[2:3]
	v_or_b32_e32 v143, 48, v162
	v_add_u32_e32 v82, s0, v143
	s_waitcnt lgkmcnt(0)
	v_ashrrev_i32_e32 v83, 31, v82
	v_lshlrev_b64 v[148:149], 12, v[82:83]
	v_lshl_add_u64 v[148:149], s[70:71], 0, v[148:149]
	v_lshl_add_u64 v[148:149], v[148:149], 0, v[140:141]
	v_mov_b64_e32 v[150:151], v[234:235]
	v_mov_b64_e32 v[152:153], v[236:237]
	v_mov_b64_e32 v[154:155], v[238:239]
	v_mov_b64_e32 v[148:149], v[240:241]
	s_nop 0
	v_fmac_f32_e32 v138, 0x3a000000, v139
	v_rcp_f32_e32 v138, v138
	s_waitcnt vmcnt(3)
	v_lshlrev_b32_e32 v156, 16, v150
	v_and_b32_e32 v157, 0xffff0000, v150
	v_lshlrev_b32_e32 v150, 16, v151
	v_and_b32_e32 v151, 0xffff0000, v151
	s_waitcnt vmcnt(2)
	v_lshlrev_b32_e32 v158, 16, v152
	v_and_b32_e32 v159, 0xffff0000, v152
	v_lshlrev_b32_e32 v152, 16, v153
	v_and_b32_e32 v153, 0xffff0000, v153
	s_waitcnt vmcnt(1)
	v_lshlrev_b32_e32 v164, 16, v154
	v_and_b32_e32 v165, 0xffff0000, v154
	v_lshlrev_b32_e32 v154, 16, v155
	v_and_b32_e32 v155, 0xffff0000, v155
	s_waitcnt vmcnt(0)
	v_lshlrev_b32_e32 v166, 16, v148
	v_and_b32_e32 v167, 0xffff0000, v148
	v_lshlrev_b32_e32 v148, 16, v149
	v_and_b32_e32 v149, 0xffff0000, v149
	v_pk_fma_f32 v[80:81], v[80:81], v[138:139], v[150:151] op_sel_hi:[1,0,1]
	v_pk_fma_f32 v[78:79], v[78:79], v[138:139], v[156:157] op_sel_hi:[1,0,1]
	v_pk_fma_f32 v[76:77], v[76:77], v[138:139], v[152:153] op_sel_hi:[1,0,1]
	v_pk_fma_f32 v[74:75], v[74:75], v[138:139], v[158:159] op_sel_hi:[1,0,1]
	v_pk_fma_f32 v[72:73], v[72:73], v[138:139], v[154:155] op_sel_hi:[1,0,1]
	v_pk_fma_f32 v[70:71], v[70:71], v[138:139], v[164:165] op_sel_hi:[1,0,1]
	v_pk_fma_f32 v[68:69], v[68:69], v[138:139], v[148:149] op_sel_hi:[1,0,1]
	v_pk_fma_f32 v[66:67], v[66:67], v[138:139], v[166:167] op_sel_hi:[1,0,1]
	v_mul_f32_e32 v138, v79, v79
	v_mul_f32_e32 v139, v81, v81
	v_mul_f32_e32 v141, v75, v75
	v_mul_f32_e32 v145, v77, v77
	v_mul_f32_e32 v147, v71, v71
	v_mul_f32_e32 v148, v73, v73
	v_fmac_f32_e32 v138, v78, v78
	v_fmac_f32_e32 v139, v80, v80
	v_fmac_f32_e32 v141, v74, v74
	v_fmac_f32_e32 v145, v76, v76
	v_mul_f32_e32 v149, v67, v67
	v_mul_f32_e32 v150, v69, v69
	v_fmac_f32_e32 v147, v70, v70
	v_fmac_f32_e32 v148, v72, v72
	v_add_f32_e32 v138, v138, v139
	v_add_f32_e32 v139, v141, v145
	v_fmac_f32_e32 v149, v66, v66
	v_fmac_f32_e32 v150, v68, v68
	v_add_f32_e32 v141, v147, v148
	v_add_f32_e32 v138, v138, v139
	v_add_f32_e32 v138, v138, v141
	v_add_f32_e32 v139, v149, v150
	v_add_f32_e32 v138, v138, v139
	v_mov_b32_e32 v139, v138
	s_nop 1
	v_permlane16_swap_b32_e32 v139, v138
	s_waitcnt lgkmcnt(0)
	v_add_f32_e32 v138, v138, v139
	v_mov_b32_e32 v139, v138
	s_nop 1
	v_permlane32_swap_b32_e32 v139, v138
	s_and_saveexec_b64 s[2:3], vcc
	s_cbranch_execz .LBB0_1042
	v_lshl_add_u32 v141, v143, 4, s1
	s_waitcnt lgkmcnt(0)
	v_add_f32_e32 v138, v138, v139
	ds_write_b32 v141, v138
.LBB0_1042:
	s_or_b64 exec, exec, s[2:3]
	v_add_u32_e32 v143, 0x80, v162
	v_add_u32_e32 v138, s0, v143
	s_waitcnt lgkmcnt(0)
	v_ashrrev_i32_e32 v139, 31, v138
	v_lshlrev_b64 v[148:149], 12, v[138:139]
	v_lshl_add_u64 v[148:149], s[70:71], 0, v[148:149]
	v_mov_b32_e32 v141, 0
	v_lshl_add_u64 v[148:149], v[148:149], 0, v[140:141]
	v_mov_b64_e32 v[150:151], v[244:245]
	v_mov_b64_e32 v[152:153], v[246:247]
	v_mov_b64_e32 v[154:155], v[248:249]
	v_mov_b64_e32 v[148:149], v[250:251]
	s_nop 0
	v_mov_b32_e32 v145, 0x3727c5ac
	v_fmamk_f32 v142, v142, 0x3a000000, v145
	v_rcp_f32_e32 v142, v142
	s_waitcnt vmcnt(3)
	v_lshlrev_b32_e32 v156, 16, v150
	v_and_b32_e32 v157, 0xffff0000, v150
	v_lshlrev_b32_e32 v150, 16, v151
	v_and_b32_e32 v151, 0xffff0000, v151
	s_waitcnt vmcnt(2)
	v_lshlrev_b32_e32 v158, 16, v152
	v_and_b32_e32 v159, 0xffff0000, v152
	v_lshlrev_b32_e32 v152, 16, v153
	v_and_b32_e32 v153, 0xffff0000, v153
	s_waitcnt vmcnt(1)
	v_lshlrev_b32_e32 v164, 16, v154
	v_and_b32_e32 v165, 0xffff0000, v154
	v_lshlrev_b32_e32 v154, 16, v155
	v_and_b32_e32 v155, 0xffff0000, v155
	s_waitcnt vmcnt(0)
	v_lshlrev_b32_e32 v166, 16, v148
	v_and_b32_e32 v167, 0xffff0000, v148
	v_lshlrev_b32_e32 v148, 16, v149
	v_and_b32_e32 v149, 0xffff0000, v149
	v_pk_fma_f32 v[64:65], v[64:65], v[142:143], v[150:151] op_sel_hi:[1,0,1]
	v_pk_fma_f32 v[62:63], v[62:63], v[142:143], v[156:157] op_sel_hi:[1,0,1]
	v_pk_fma_f32 v[60:61], v[60:61], v[142:143], v[152:153] op_sel_hi:[1,0,1]
	v_pk_fma_f32 v[58:59], v[58:59], v[142:143], v[158:159] op_sel_hi:[1,0,1]
	v_pk_fma_f32 v[56:57], v[56:57], v[142:143], v[154:155] op_sel_hi:[1,0,1]
	v_pk_fma_f32 v[54:55], v[54:55], v[142:143], v[164:165] op_sel_hi:[1,0,1]
	v_pk_fma_f32 v[52:53], v[52:53], v[142:143], v[148:149] op_sel_hi:[1,0,1]
	v_pk_fma_f32 v[50:51], v[50:51], v[142:143], v[166:167] op_sel_hi:[1,0,1]
	v_mul_f32_e32 v142, v63, v63
	v_mul_f32_e32 v147, v65, v65
	v_mul_f32_e32 v148, v59, v59
	v_mul_f32_e32 v149, v61, v61
	v_mul_f32_e32 v150, v55, v55
	v_mul_f32_e32 v151, v57, v57
	v_fmac_f32_e32 v142, v62, v62
	v_fmac_f32_e32 v147, v64, v64
	v_fmac_f32_e32 v148, v58, v58
	v_fmac_f32_e32 v149, v60, v60
	v_mul_f32_e32 v152, v51, v51
	v_mul_f32_e32 v153, v53, v53
	v_fmac_f32_e32 v150, v54, v54
	v_fmac_f32_e32 v151, v56, v56
	v_add_f32_e32 v142, v142, v147
	v_add_f32_e32 v147, v148, v149
	v_fmac_f32_e32 v152, v50, v50
	v_fmac_f32_e32 v153, v52, v52
	v_add_f32_e32 v148, v150, v151
	v_add_f32_e32 v142, v142, v147
	v_add_f32_e32 v142, v142, v148
	v_add_f32_e32 v147, v152, v153
	v_add_f32_e32 v142, v142, v147
	v_mov_b32_e32 v147, v142
	s_nop 1
	v_permlane16_swap_b32_e32 v147, v142
	s_waitcnt lgkmcnt(0)
	v_add_f32_e32 v142, v142, v147
	v_mov_b32_e32 v147, v142
	s_nop 1
	v_permlane32_swap_b32_e32 v147, v142
	s_and_saveexec_b64 s[2:3], vcc
	s_cbranch_execz .LBB0_1044
	v_lshl_add_u32 v143, v143, 4, s1
	s_waitcnt lgkmcnt(0)
	v_add_f32_e32 v142, v142, v147
	ds_write_b32 v143, v142
; __device__ __forceinline__ f32x4 bf4_to_f32(u32x2 w) { f32x4 r; r[0] = __uint_as_float(w.x << 16); r[1] = __uint_as_float(w.x & 0xffff0000u); r[2] = __uint_as_float(w.y << 16); r[3] = __uint_as_float(w.y & 0xffff0000u); return r; }
;     __device__ __forceinline__ void fused(f32x4 (&acc)[2][2][4][2], const Unit& u, int wr, int wc, int fr, int fq, PG8_LAS unsigned char* lds, int wid, int lane) const {
;     ...
;             for (int m = 0; m < 4; ++m) { const int r = ai * HALF + wr * 64 + m * 16 + fr; const size_t off = (size_t)(u.pm * BM + r) * 2048 + col0; float s = 0.f;
;                 const float rr = __builtin_amdgcn_rcpf(r2[ai * 4 + m] * (1.0f / 2048.0f) + 1e-5f);
; #pragma unroll
;                 for (int bj = 0; bj < 2; ++bj)
; #pragma unroll
;                     for (int n = 0; n < 2; ++n) { const f32x4 bs = bf4_to_f32(*(const u32x2*)(base + off + bj * HALF + n * 16)); const f32x4 o = bs + acc[ai][bj][m][n] * rr; acc[ai][bj][m][n] = o;
;                         s += (o[0] * o[0] + o[1] * o[1]) + (o[2] * o[2] + o[3] * o[3]); }
;                 s += __shfl_xor(s, 16); s += __shfl_xor(s, 32);
;                 if (fq == 0) P[r * 4 + wc] = s; }
.LBB0_1044:
	s_or_b64 exec, exec, s[2:3]
	s_waitcnt lgkmcnt(0)
	v_add_u32_e32 v147, 0x90, v162
	v_add_u32_e32 v142, s0, v147
	v_ashrrev_i32_e32 v143, 31, v142
	v_lshlrev_b64 v[148:149], 12, v[142:143]
	v_lshl_add_u64 v[148:149], s[70:71], 0, v[148:149]
	v_lshl_add_u64 v[148:149], v[148:149], 0, v[140:141]
	v_mov_b64_e32 v[150:151], v[252:253]
	v_mov_b64_e32 v[152:153], v[254:255]
	v_mov_b64_e32 v[154:155], v[216:217]
	v_mov_b64_e32 v[148:149], v[192:193]
	s_nop 0
	v_fmac_f32_e32 v145, 0x3a000000, v144
	v_rcp_f32_e32 v144, v145
	s_waitcnt vmcnt(3)
	v_lshlrev_b32_e32 v156, 16, v150
	v_and_b32_e32 v157, 0xffff0000, v150
	v_lshlrev_b32_e32 v150, 16, v151
	v_and_b32_e32 v151, 0xffff0000, v151
	s_waitcnt vmcnt(2)
	v_lshlrev_b32_e32 v158, 16, v152
	v_and_b32_e32 v159, 0xffff0000, v152
	v_lshlrev_b32_e32 v152, 16, v153
	v_and_b32_e32 v153, 0xffff0000, v153
	s_waitcnt vmcnt(1)
	v_lshlrev_b32_e32 v164, 16, v154
	v_and_b32_e32 v165, 0xffff0000, v154
	v_lshlrev_b32_e32 v154, 16, v155
	v_and_b32_e32 v155, 0xffff0000, v155
	s_waitcnt vmcnt(0)
	v_lshlrev_b32_e32 v166, 16, v148
	v_and_b32_e32 v167, 0xffff0000, v148
	v_lshlrev_b32_e32 v148, 16, v149
	v_and_b32_e32 v149, 0xffff0000, v149
	v_pk_fma_f32 v[48:49], v[48:49], v[144:145], v[150:151] op_sel_hi:[1,0,1]
	v_pk_fma_f32 v[46:47], v[46:47], v[144:145], v[156:157] op_sel_hi:[1,0,1]
	v_pk_fma_f32 v[44:45], v[44:45], v[144:145], v[152:153] op_sel_hi:[1,0,1]
	v_pk_fma_f32 v[42:43], v[42:43], v[144:145], v[158:159] op_sel_hi:[1,0,1]
	v_pk_fma_f32 v[40:41], v[40:41], v[144:145], v[154:155] op_sel_hi:[1,0,1]
	v_pk_fma_f32 v[38:39], v[38:39], v[144:145], v[164:165] op_sel_hi:[1,0,1]
	v_pk_fma_f32 v[36:37], v[36:37], v[144:145], v[148:149] op_sel_hi:[1,0,1]
	v_pk_fma_f32 v[34:35], v[34:35], v[144:145], v[166:167] op_sel_hi:[1,0,1]
	v_mul_f32_e32 v141, v47, v47
	v_mul_f32_e32 v144, v49, v49
	v_mul_f32_e32 v145, v43, v43
	v_mul_f32_e32 v148, v45, v45
	v_mul_f32_e32 v149, v39, v39
	v_mul_f32_e32 v150, v41, v41
	v_fmac_f32_e32 v141, v46, v46
	v_fmac_f32_e32 v144, v48, v48
	v_fmac_f32_e32 v145, v42, v42
	v_fmac_f32_e32 v148, v44, v44
	v_mul_f32_e32 v151, v35, v35
	v_mul_f32_e32 v152, v37, v37
	v_fmac_f32_e32 v149, v38, v38
	v_fmac_f32_e32 v150, v40, v40
	v_add_f32_e32 v141, v141, v144
	v_add_f32_e32 v144, v145, v148
	v_fmac_f32_e32 v151, v34, v34
	v_fmac_f32_e32 v152, v36, v36
	v_add_f32_e32 v145, v149, v150
	v_add_f32_e32 v141, v141, v144
	v_add_f32_e32 v141, v141, v145
	v_add_f32_e32 v144, v151, v152
	v_add_f32_e32 v141, v141, v144
	v_mov_b32_e32 v144, v141
	s_nop 1
	v_permlane16_swap_b32_e32 v144, v141
	s_waitcnt lgkmcnt(0)
	v_add_f32_e32 v141, v141, v144
	v_mov_b32_e32 v144, v141
	s_nop 1
	v_permlane32_swap_b32_e32 v144, v141
	s_and_saveexec_b64 s[2:3], vcc
	s_cbranch_execz .LBB0_1046
	v_lshl_add_u32 v145, v147, 4, s1
	s_waitcnt lgkmcnt(0)
	v_add_f32_e32 v141, v141, v144
	ds_write_b32 v145, v141
; __device__ __forceinline__ f32x4 bf4_to_f32(u32x2 w) { f32x4 r; r[0] = __uint_as_float(w.x << 16); r[1] = __uint_as_float(w.x & 0xffff0000u); r[2] = __uint_as_float(w.y << 16); r[3] = __uint_as_float(w.y & 0xffff0000u); return r; }
;     __device__ __forceinline__ void fused(f32x4 (&acc)[2][2][4][2], const Unit& u, int wr, int wc, int fr, int fq, PG8_LAS unsigned char* lds, int wid, int lane) const {
;     ...
;             for (int m = 0; m < 4; ++m) { const int r = ai * HALF + wr * 64 + m * 16 + fr; const size_t off = (size_t)(u.pm * BM + r) * 2048 + col0; float s = 0.f;
;                 const float rr = __builtin_amdgcn_rcpf(r2[ai * 4 + m] * (1.0f / 2048.0f) + 1e-5f);
; #pragma unroll
;                 for (int bj = 0; bj < 2; ++bj)
; #pragma unroll
;                     for (int n = 0; n < 2; ++n) { const f32x4 bs = bf4_to_f32(*(const u32x2*)(base + off + bj * HALF + n * 16)); const f32x4 o = bs + acc[ai][bj][m][n] * rr; acc[ai][bj][m][n] = o;
;                         s += (o[0] * o[0] + o[1] * o[1]) + (o[2] * o[2] + o[3] * o[3]); }
;                 s += __shfl_xor(s, 16); s += __shfl_xor(s, 32);
;                 if (fq == 0) P[r * 4 + wc] = s; }
.LBB0_1046:
	s_or_b64 exec, exec, s[2:3]
	v_add_u32_e32 v147, 0xa0, v162
	s_waitcnt lgkmcnt(0)
	v_add_u32_e32 v144, s0, v147
	v_ashrrev_i32_e32 v145, 31, v144
	v_lshlrev_b64 v[148:149], 12, v[144:145]
	v_lshl_add_u64 v[148:149], s[70:71], 0, v[148:149]
	v_mov_b32_e32 v141, 0
	v_lshl_add_u64 v[148:149], v[148:149], 0, v[140:141]
	s_waitcnt vmcnt(0)
	v_mov_b64_e32 v[150:151], v[196:197]
	v_mov_b64_e32 v[152:153], v[198:199]
	v_mov_b64_e32 v[154:155], v[200:201]
	v_mov_b64_e32 v[156:157], v[202:203]
	v_mov_b32_e32 v148, 0x3727c5ac
	v_fmamk_f32 v146, v146, 0x3a000000, v148
	v_rcp_f32_e32 v146, v146
	s_waitcnt vmcnt(3)
	v_lshlrev_b32_e32 v158, 16, v150
	v_and_b32_e32 v159, 0xffff0000, v150
	v_lshlrev_b32_e32 v150, 16, v151
	v_and_b32_e32 v151, 0xffff0000, v151
	s_waitcnt vmcnt(2)
	v_lshlrev_b32_e32 v164, 16, v152
	v_and_b32_e32 v165, 0xffff0000, v152
	v_lshlrev_b32_e32 v152, 16, v153
	v_and_b32_e32 v153, 0xffff0000, v153
	s_waitcnt vmcnt(1)
	v_lshlrev_b32_e32 v166, 16, v154
	v_and_b32_e32 v167, 0xffff0000, v154
	v_lshlrev_b32_e32 v154, 16, v155
	v_and_b32_e32 v155, 0xffff0000, v155
	s_waitcnt vmcnt(0)
	v_lshlrev_b32_e32 v168, 16, v156
	v_and_b32_e32 v169, 0xffff0000, v156
	v_lshlrev_b32_e32 v156, 16, v157
	v_and_b32_e32 v157, 0xffff0000, v157
	v_pk_fma_f32 v[32:33], v[32:33], v[146:147], v[150:151] op_sel_hi:[1,0,1]
	v_pk_fma_f32 v[30:31], v[30:31], v[146:147], v[158:159] op_sel_hi:[1,0,1]
	v_pk_fma_f32 v[28:29], v[28:29], v[146:147], v[152:153] op_sel_hi:[1,0,1]
	v_pk_fma_f32 v[26:27], v[26:27], v[146:147], v[164:165] op_sel_hi:[1,0,1]
	v_pk_fma_f32 v[24:25], v[24:25], v[146:147], v[154:155] op_sel_hi:[1,0,1]
	v_pk_fma_f32 v[22:23], v[22:23], v[146:147], v[166:167] op_sel_hi:[1,0,1]
	v_pk_fma_f32 v[20:21], v[20:21], v[146:147], v[156:157] op_sel_hi:[1,0,1]
	v_pk_fma_f32 v[18:19], v[18:19], v[146:147], v[168:169] op_sel_hi:[1,0,1]
	v_mul_f32_e32 v146, v31, v31
	v_mul_f32_e32 v149, v33, v33
	v_mul_f32_e32 v150, v27, v27
	v_mul_f32_e32 v151, v29, v29
	v_mul_f32_e32 v152, v23, v23
	v_mul_f32_e32 v153, v25, v25
	v_fmac_f32_e32 v146, v30, v30
	v_fmac_f32_e32 v149, v32, v32
	v_fmac_f32_e32 v150, v26, v26
	v_fmac_f32_e32 v151, v28, v28
	v_mul_f32_e32 v154, v19, v19
	v_mul_f32_e32 v155, v21, v21
	v_fmac_f32_e32 v152, v22, v22
	v_fmac_f32_e32 v153, v24, v24
	v_add_f32_e32 v146, v146, v149
	v_add_f32_e32 v149, v150, v151
	v_fmac_f32_e32 v154, v18, v18
	v_fmac_f32_e32 v155, v20, v20
	v_add_f32_e32 v150, v152, v153
	v_add_f32_e32 v146, v146, v149
	v_add_f32_e32 v146, v146, v150
	v_add_f32_e32 v149, v154, v155
	v_add_f32_e32 v146, v146, v149
	v_mov_b32_e32 v149, v146
	s_nop 1
	v_permlane16_swap_b32_e32 v149, v146
	s_waitcnt lgkmcnt(0)
	v_add_f32_e32 v146, v146, v149
	v_mov_b32_e32 v149, v146
	s_nop 1
	v_permlane32_swap_b32_e32 v149, v146
	s_and_saveexec_b64 s[2:3], vcc
	s_cbranch_execz .LBB0_1048
	v_lshl_add_u32 v147, v147, 4, s1
	s_waitcnt lgkmcnt(0)
	v_add_f32_e32 v146, v146, v149
	ds_write_b32 v147, v146
.LBB0_1048:
	s_or_b64 exec, exec, s[2:3]
	v_add_u32_e32 v164, 0xb0, v162
	v_add_u32_e32 v146, s0, v164
	v_ashrrev_i32_e32 v147, 31, v146
	v_lshlrev_b64 v[150:151], 12, v[146:147]
	v_lshl_add_u64 v[150:151], s[70:71], 0, v[150:151]
	v_lshl_add_u64 v[140:141], v[150:151], 0, v[140:141]
	s_waitcnt vmcnt(0)
	v_mov_b64_e32 v[150:151], v[204:205]
	v_mov_b64_e32 v[152:153], v[206:207]
	v_mov_b64_e32 v[154:155], v[208:209]
	v_mov_b64_e32 v[140:141], v[210:211]
	s_nop 0
	v_fmac_f32_e32 v148, 0x3a000000, v1
	v_rcp_f32_e32 v148, v148
	s_waitcnt vmcnt(3)
	v_lshlrev_b32_e32 v158, 16, v150
	v_and_b32_e32 v159, 0xffff0000, v150
	v_lshlrev_b32_e32 v150, 16, v151
	v_and_b32_e32 v151, 0xffff0000, v151
	s_waitcnt vmcnt(2)
	v_lshlrev_b32_e32 v166, 16, v152
	v_and_b32_e32 v167, 0xffff0000, v152
	v_lshlrev_b32_e32 v152, 16, v153
	v_and_b32_e32 v153, 0xffff0000, v153
	s_waitcnt vmcnt(1)
	v_lshlrev_b32_e32 v168, 16, v154
	v_and_b32_e32 v169, 0xffff0000, v154
	v_lshlrev_b32_e32 v170, 16, v155
	v_and_b32_e32 v171, 0xffff0000, v155
	s_waitcnt vmcnt(0)
	v_lshlrev_b32_e32 v172, 16, v140
	v_and_b32_e32 v173, 0xffff0000, v140
	v_lshlrev_b32_e32 v174, 16, v141
	v_and_b32_e32 v175, 0xffff0000, v141
	s_waitcnt lgkmcnt(0)
	v_pk_fma_f32 v[156:157], v[16:17], v[148:149], v[150:151] op_sel_hi:[1,0,1]
	v_pk_fma_f32 v[158:159], v[14:15], v[148:149], v[158:159] op_sel_hi:[1,0,1]
	v_pk_fma_f32 v[152:153], v[12:13], v[148:149], v[152:153] op_sel_hi:[1,0,1]
	v_pk_fma_f32 v[154:155], v[10:11], v[148:149], v[166:167] op_sel_hi:[1,0,1]
	v_pk_fma_f32 v[140:141], v[8:9], v[148:149], v[170:171] op_sel_hi:[1,0,1]
	v_pk_fma_f32 v[150:151], v[6:7], v[148:149], v[168:169] op_sel_hi:[1,0,1]
	v_pk_fma_f32 v[16:17], v[4:5], v[148:149], v[174:175] op_sel_hi:[1,0,1]
	v_pk_fma_f32 v[148:149], v[2:3], v[148:149], v[172:173] op_sel_hi:[1,0,1]
	v_mul_f32_e32 v1, v159, v159
	v_mul_f32_e32 v2, v157, v157
	v_mul_f32_e32 v3, v155, v155
	v_mul_f32_e32 v4, v153, v153
	v_mul_f32_e32 v5, v151, v151
	v_mul_f32_e32 v6, v141, v141
	v_fmac_f32_e32 v1, v158, v158
	v_fmac_f32_e32 v2, v156, v156
	v_fmac_f32_e32 v3, v154, v154
	v_fmac_f32_e32 v4, v152, v152
	v_mul_f32_e32 v7, v149, v149
	v_mul_f32_e32 v8, v17, v17
	v_fmac_f32_e32 v5, v150, v150
	v_fmac_f32_e32 v6, v140, v140
	v_add_f32_e32 v1, v1, v2
	v_add_f32_e32 v2, v3, v4
	v_fmac_f32_e32 v7, v148, v148
	v_fmac_f32_e32 v8, v16, v16
	v_add_f32_e32 v3, v5, v6
	v_add_f32_e32 v1, v1, v2
	v_add_f32_e32 v1, v1, v3
	v_add_f32_e32 v2, v7, v8
	v_add_f32_e32 v1, v1, v2
	v_mov_b32_e32 v2, v1
	s_nop 1
	v_permlane16_swap_b32_e32 v2, v1
	s_waitcnt lgkmcnt(0)
	v_add_f32_e32 v1, v1, v2
	v_mov_b32_e32 v2, v1
	s_nop 1
	v_permlane32_swap_b32_e32 v2, v1
	s_and_saveexec_b64 s[2:3], vcc
	s_cbranch_execz .LBB0_1050
	v_lshl_add_u32 v3, v164, 4, s1
	s_waitcnt lgkmcnt(0)
	v_add_f32_e32 v1, v1, v2
	ds_write_b32 v3, v1
